# GEMM K-loops: saddr-form LDS-DMA (no 64-bit VALU address adds), DMA issue interleaved between ds_reads
# speedup vs baseline: 1.0072x; 1.0072x over previous
.LBB0_341:
	s_add_u32 s14, s12, 0xfff00080
	s_addc_u32 s15, s13, -1
	s_add_i32 s30, 0, 0x10000
	s_cmp_eq_u32 s39, 60
	s_cselect_b32 s17, s51, s15
	s_cselect_b32 s16, s50, s14
	v_add_u32_e32 v130, s30, v159
	s_cselect_b32 s15, s53, s1
	s_cselect_b32 s14, s52, s0
	s_add_i32 s42, 0, 0x14000
	s_add_i32 m0, s8, 0xc000
	ds_read_b128 v[152:155], v130
	ds_read_b128 v[162:165], v130 offset:1024
	global_load_lds_dwordx4 v148, s[12:13]
	s_add_i32 m0, s8, 0xe000
	ds_read_b128 v[166:169], v130 offset:2048
	ds_read_b128 v[170:173], v130 offset:3072
	global_load_lds_dwordx4 v150, s[12:13]
	v_add_u32_e32 v130, s42, v159
	ds_read_b128 v[174:177], v130
	ds_read_b128 v[182:185], v130 offset:1024
	ds_read_b128 v[186:189], v130 offset:2048
	ds_read_b128 v[190:193], v130 offset:3072
	ds_read_b128 v[194:197], v161
	ds_read_b128 v[198:201], v161 offset:1024
	ds_read_b128 v[202:205], v161 offset:2048
	ds_read_b128 v[206:209], v161 offset:3072
	ds_read_b128 v[210:213], v161 offset:4096
	ds_read_b128 v[214:217], v161 offset:5120
	ds_read_b128 v[218:221], v161 offset:6144
	ds_read_b128 v[222:225], v161 offset:7168
	s_waitcnt vmcnt(8)
	s_waitcnt lgkmcnt(0)
	s_barrier
	s_setprio 1
	s_waitcnt lgkmcnt(0)
	v_mfma_f32_16x16x32_bf16 v[126:129], v[152:155], v[194:197], v[126:129]
	v_mfma_f32_16x16x32_bf16 v[122:125], v[166:169], v[194:197], v[122:125]
	v_mfma_f32_16x16x32_bf16 v[110:113], v[152:155], v[202:205], v[110:113]
	v_mfma_f32_16x16x32_bf16 v[106:109], v[166:169], v[202:205], v[106:109]
	v_mfma_f32_16x16x32_bf16 v[94:97], v[152:155], v[210:213], v[94:97]
	v_mfma_f32_16x16x32_bf16 v[90:93], v[166:169], v[210:213], v[90:93]
	v_mfma_f32_16x16x32_bf16 v[78:81], v[152:155], v[218:221], v[78:81]
	v_mfma_f32_16x16x32_bf16 v[74:77], v[166:169], v[218:221], v[74:77]
	v_mfma_f32_16x16x32_bf16 v[126:129], v[162:165], v[198:201], v[126:129]
	v_mfma_f32_16x16x32_bf16 v[122:125], v[170:173], v[198:201], v[122:125]
	v_mfma_f32_16x16x32_bf16 v[110:113], v[162:165], v[206:209], v[110:113]
	v_mfma_f32_16x16x32_bf16 v[106:109], v[170:173], v[206:209], v[106:109]
	v_mfma_f32_16x16x32_bf16 v[94:97], v[162:165], v[214:217], v[94:97]
	v_mfma_f32_16x16x32_bf16 v[90:93], v[170:173], v[214:217], v[90:93]
	v_mfma_f32_16x16x32_bf16 v[78:81], v[162:165], v[222:225], v[78:81]
	v_mfma_f32_16x16x32_bf16 v[74:77], v[170:173], v[222:225], v[74:77]
	s_setprio 0
	s_setprio 1
	v_mfma_f32_16x16x32_bf16 v[118:121], v[174:177], v[194:197], v[118:121]
	v_mfma_f32_16x16x32_bf16 v[114:117], v[186:189], v[194:197], v[114:117]
	v_mfma_f32_16x16x32_bf16 v[102:105], v[174:177], v[202:205], v[102:105]
	v_mfma_f32_16x16x32_bf16 v[98:101], v[186:189], v[202:205], v[98:101]
	v_mfma_f32_16x16x32_bf16 v[86:89], v[174:177], v[210:213], v[86:89]
	v_mfma_f32_16x16x32_bf16 v[82:85], v[186:189], v[210:213], v[82:85]
	v_mfma_f32_16x16x32_bf16 v[70:73], v[174:177], v[218:221], v[70:73]
	v_mfma_f32_16x16x32_bf16 v[66:69], v[186:189], v[218:221], v[66:69]
	v_mfma_f32_16x16x32_bf16 v[118:121], v[182:185], v[198:201], v[118:121]
	v_mfma_f32_16x16x32_bf16 v[114:117], v[190:193], v[198:201], v[114:117]
	v_mfma_f32_16x16x32_bf16 v[102:105], v[182:185], v[206:209], v[102:105]
	v_mfma_f32_16x16x32_bf16 v[98:101], v[190:193], v[206:209], v[98:101]
	v_mfma_f32_16x16x32_bf16 v[86:89], v[182:185], v[214:217], v[86:89]
	v_mfma_f32_16x16x32_bf16 v[82:85], v[190:193], v[214:217], v[82:85]
	v_mfma_f32_16x16x32_bf16 v[70:73], v[182:185], v[222:225], v[70:73]
	v_mfma_f32_16x16x32_bf16 v[66:69], v[190:193], v[222:225], v[66:69]
	s_setprio 0
	s_barrier
	s_add_i32 m0, s28, 0x10000
	ds_read_b128 v[194:197], v161 offset:16384
	ds_read_b128 v[198:201], v161 offset:17408
	global_load_lds_dwordx4 v144, s[14:15]
	s_add_i32 m0, s28, 0x12000
	s_add_u32 s98, s14, 0x100000
	s_addc_u32 s99, s15, 0
	ds_read_b128 v[202:205], v161 offset:18432
	global_load_lds_dwordx4 v140, s[14:15]
	s_add_i32 m0, s28, 0x14000
	ds_read_b128 v[206:209], v161 offset:19456
	ds_read_b128 v[210:213], v161 offset:20480
	global_load_lds_dwordx4 v144, s[98:99]
	s_add_i32 m0, s28, 0x16000
	ds_read_b128 v[214:217], v161 offset:21504
	ds_read_b128 v[218:221], v161 offset:22528
	global_load_lds_dwordx4 v140, s[98:99]
	s_mov_b32 m0, s8
	ds_read_b128 v[222:225], v161 offset:23552
	global_load_lds_dwordx4 v146, s[16:17]
	s_mov_b32 m0, s9
	s_nop 0
	global_load_lds_dwordx4 v142, s[16:17]
	s_waitcnt vmcnt(8)
	s_waitcnt lgkmcnt(0)
	s_barrier
	s_setprio 1
	s_waitcnt lgkmcnt(0)
	v_mfma_f32_16x16x32_bf16 v[62:65], v[152:155], v[194:197], v[62:65]
	v_mfma_f32_16x16x32_bf16 v[58:61], v[166:169], v[194:197], v[58:61]
	v_mfma_f32_16x16x32_bf16 v[46:49], v[152:155], v[202:205], v[46:49]
	v_mfma_f32_16x16x32_bf16 v[42:45], v[166:169], v[202:205], v[42:45]
	v_mfma_f32_16x16x32_bf16 v[30:33], v[152:155], v[210:213], v[30:33]
	v_mfma_f32_16x16x32_bf16 v[26:29], v[166:169], v[210:213], v[26:29]
	v_mfma_f32_16x16x32_bf16 v[14:17], v[152:155], v[218:221], v[14:17]
	v_mfma_f32_16x16x32_bf16 v[10:13], v[166:169], v[218:221], v[10:13]
	v_mfma_f32_16x16x32_bf16 v[62:65], v[162:165], v[198:201], v[62:65]
	v_mfma_f32_16x16x32_bf16 v[58:61], v[170:173], v[198:201], v[58:61]
	v_mfma_f32_16x16x32_bf16 v[46:49], v[162:165], v[206:209], v[46:49]
	v_mfma_f32_16x16x32_bf16 v[42:45], v[170:173], v[206:209], v[42:45]
	v_mfma_f32_16x16x32_bf16 v[30:33], v[162:165], v[214:217], v[30:33]
	v_mfma_f32_16x16x32_bf16 v[26:29], v[170:173], v[214:217], v[26:29]
	v_mfma_f32_16x16x32_bf16 v[14:17], v[162:165], v[222:225], v[14:17]
	v_mfma_f32_16x16x32_bf16 v[10:13], v[170:173], v[222:225], v[10:13]
	s_setprio 0
	s_setprio 1
	v_mfma_f32_16x16x32_bf16 v[54:57], v[174:177], v[194:197], v[54:57]
	v_mfma_f32_16x16x32_bf16 v[50:53], v[186:189], v[194:197], v[50:53]
	v_mfma_f32_16x16x32_bf16 v[38:41], v[174:177], v[202:205], v[38:41]
	v_mfma_f32_16x16x32_bf16 v[34:37], v[186:189], v[202:205], v[34:37]
	v_mfma_f32_16x16x32_bf16 v[22:25], v[174:177], v[210:213], v[22:25]
	v_mfma_f32_16x16x32_bf16 v[18:21], v[186:189], v[210:213], v[18:21]
	v_mfma_f32_16x16x32_bf16 v[6:9], v[174:177], v[218:221], v[6:9]
	v_mfma_f32_16x16x32_bf16 v[2:5], v[186:189], v[218:221], v[2:5]
	v_mfma_f32_16x16x32_bf16 v[54:57], v[182:185], v[198:201], v[54:57]
	v_mfma_f32_16x16x32_bf16 v[50:53], v[190:193], v[198:201], v[50:53]
	v_mfma_f32_16x16x32_bf16 v[38:41], v[182:185], v[206:209], v[38:41]
	v_mfma_f32_16x16x32_bf16 v[34:37], v[190:193], v[206:209], v[34:37]
	v_mfma_f32_16x16x32_bf16 v[22:25], v[182:185], v[214:217], v[22:25]
	v_mfma_f32_16x16x32_bf16 v[18:21], v[190:193], v[214:217], v[18:21]
	v_mfma_f32_16x16x32_bf16 v[6:9], v[182:185], v[222:225], v[6:9]
	v_mfma_f32_16x16x32_bf16 v[2:5], v[190:193], v[222:225], v[2:5]
	s_setprio 0
	s_barrier
	s_add_u32 s100, s16, 0x100000
	s_addc_u32 s101, s17, 0
	s_mov_b32 m0, s29
	s_add_i32 s30, 0, 0x18000
	v_add_u32_e32 v130, s30, v159
	s_add_i32 s31, 0, 0x1c000
	ds_read_b128 v[152:155], v130
	ds_read_b128 v[162:165], v130 offset:1024
	global_load_lds_dwordx4 v146, s[100:101]
	s_mov_b32 m0, s36
	ds_read_b128 v[166:169], v130 offset:2048
	ds_read_b128 v[170:173], v130 offset:3072
	global_load_lds_dwordx4 v142, s[100:101]
	v_add_u32_e32 v130, s31, v159
	ds_read_b128 v[174:177], v130
	ds_read_b128 v[182:185], v130 offset:1024
	ds_read_b128 v[186:189], v130 offset:2048
	ds_read_b128 v[190:193], v130 offset:3072
	ds_read_b128 v[194:197], v161 offset:32768
	ds_read_b128 v[198:201], v161 offset:33792
	ds_read_b128 v[202:205], v161 offset:34816
	ds_read_b128 v[206:209], v161 offset:35840
	ds_read_b128 v[210:213], v161 offset:36864
	ds_read_b128 v[214:217], v161 offset:37888
	ds_read_b128 v[218:221], v161 offset:38912
	ds_read_b128 v[222:225], v161 offset:39936
	s_waitcnt vmcnt(8)
	s_waitcnt lgkmcnt(0)
	s_barrier
	s_setprio 1
	s_waitcnt lgkmcnt(0)
	v_mfma_f32_16x16x32_bf16 v[126:129], v[152:155], v[194:197], v[126:129]
	v_mfma_f32_16x16x32_bf16 v[122:125], v[166:169], v[194:197], v[122:125]
	v_mfma_f32_16x16x32_bf16 v[110:113], v[152:155], v[202:205], v[110:113]
	v_mfma_f32_16x16x32_bf16 v[106:109], v[166:169], v[202:205], v[106:109]
	v_mfma_f32_16x16x32_bf16 v[94:97], v[152:155], v[210:213], v[94:97]
	v_mfma_f32_16x16x32_bf16 v[90:93], v[166:169], v[210:213], v[90:93]
	v_mfma_f32_16x16x32_bf16 v[78:81], v[152:155], v[218:221], v[78:81]
	v_mfma_f32_16x16x32_bf16 v[74:77], v[166:169], v[218:221], v[74:77]
	v_mfma_f32_16x16x32_bf16 v[126:129], v[162:165], v[198:201], v[126:129]
	v_mfma_f32_16x16x32_bf16 v[122:125], v[170:173], v[198:201], v[122:125]
	v_mfma_f32_16x16x32_bf16 v[110:113], v[162:165], v[206:209], v[110:113]
	v_mfma_f32_16x16x32_bf16 v[106:109], v[170:173], v[206:209], v[106:109]
	v_mfma_f32_16x16x32_bf16 v[94:97], v[162:165], v[214:217], v[94:97]
	v_mfma_f32_16x16x32_bf16 v[90:93], v[170:173], v[214:217], v[90:93]
	v_mfma_f32_16x16x32_bf16 v[78:81], v[162:165], v[222:225], v[78:81]
	v_mfma_f32_16x16x32_bf16 v[74:77], v[170:173], v[222:225], v[74:77]
	s_setprio 0
	s_setprio 1
	v_mfma_f32_16x16x32_bf16 v[118:121], v[174:177], v[194:197], v[118:121]
	v_mfma_f32_16x16x32_bf16 v[114:117], v[186:189], v[194:197], v[114:117]
	v_mfma_f32_16x16x32_bf16 v[102:105], v[174:177], v[202:205], v[102:105]
	v_mfma_f32_16x16x32_bf16 v[98:101], v[186:189], v[202:205], v[98:101]
	v_mfma_f32_16x16x32_bf16 v[86:89], v[174:177], v[210:213], v[86:89]
	v_mfma_f32_16x16x32_bf16 v[82:85], v[186:189], v[210:213], v[82:85]
	v_mfma_f32_16x16x32_bf16 v[70:73], v[174:177], v[218:221], v[70:73]
	v_mfma_f32_16x16x32_bf16 v[66:69], v[186:189], v[218:221], v[66:69]
	v_mfma_f32_16x16x32_bf16 v[118:121], v[182:185], v[198:201], v[118:121]
	v_mfma_f32_16x16x32_bf16 v[114:117], v[190:193], v[198:201], v[114:117]
	v_mfma_f32_16x16x32_bf16 v[102:105], v[182:185], v[206:209], v[102:105]
	v_mfma_f32_16x16x32_bf16 v[98:101], v[190:193], v[206:209], v[98:101]
	v_mfma_f32_16x16x32_bf16 v[86:89], v[182:185], v[214:217], v[86:89]
	v_mfma_f32_16x16x32_bf16 v[82:85], v[190:193], v[214:217], v[82:85]
	v_mfma_f32_16x16x32_bf16 v[70:73], v[182:185], v[222:225], v[70:73]
	v_mfma_f32_16x16x32_bf16 v[66:69], v[190:193], v[222:225], v[66:69]
	s_setprio 0
	s_barrier
	s_add_u32 s14, s14, 0x80
	s_addc_u32 s15, s15, 0
	s_add_i32 m0, s28, 0x18000
	ds_read_b128 v[194:197], v161 offset:49152
	ds_read_b128 v[198:201], v161 offset:50176
	global_load_lds_dwordx4 v144, s[14:15]
	s_add_i32 m0, s28, 0x1a000
	s_add_u32 s98, s98, 0x80
	s_addc_u32 s99, s99, 0
	ds_read_b128 v[202:205], v161 offset:51200
	global_load_lds_dwordx4 v140, s[14:15]
	s_add_i32 m0, s28, 0x1c000
	ds_read_b128 v[206:209], v161 offset:52224
	ds_read_b128 v[210:213], v161 offset:53248
	global_load_lds_dwordx4 v144, s[98:99]
	s_add_i32 m0, s28, 0x1e000
	s_add_u32 s16, s16, 0x80
	s_addc_u32 s17, s17, 0
	ds_read_b128 v[214:217], v161 offset:54272
	ds_read_b128 v[218:221], v161 offset:55296
	global_load_lds_dwordx4 v140, s[98:99]
	s_mov_b32 m0, s45
	ds_read_b128 v[222:225], v161 offset:56320
	global_load_lds_dwordx4 v146, s[16:17]
	s_mov_b32 m0, s46
	s_nop 0
	global_load_lds_dwordx4 v142, s[16:17]
	s_waitcnt vmcnt(8)
	s_waitcnt lgkmcnt(0)
	s_barrier
	s_setprio 1
	s_waitcnt lgkmcnt(0)
	v_mfma_f32_16x16x32_bf16 v[62:65], v[152:155], v[194:197], v[62:65]
	v_mfma_f32_16x16x32_bf16 v[58:61], v[166:169], v[194:197], v[58:61]
	v_mfma_f32_16x16x32_bf16 v[46:49], v[152:155], v[202:205], v[46:49]
	v_mfma_f32_16x16x32_bf16 v[42:45], v[166:169], v[202:205], v[42:45]
	v_mfma_f32_16x16x32_bf16 v[30:33], v[152:155], v[210:213], v[30:33]
	v_mfma_f32_16x16x32_bf16 v[26:29], v[166:169], v[210:213], v[26:29]
	v_mfma_f32_16x16x32_bf16 v[14:17], v[152:155], v[218:221], v[14:17]
	v_mfma_f32_16x16x32_bf16 v[10:13], v[166:169], v[218:221], v[10:13]
	v_mfma_f32_16x16x32_bf16 v[62:65], v[162:165], v[198:201], v[62:65]
	v_mfma_f32_16x16x32_bf16 v[58:61], v[170:173], v[198:201], v[58:61]
	v_mfma_f32_16x16x32_bf16 v[46:49], v[162:165], v[206:209], v[46:49]
	v_mfma_f32_16x16x32_bf16 v[42:45], v[170:173], v[206:209], v[42:45]
	v_mfma_f32_16x16x32_bf16 v[30:33], v[162:165], v[214:217], v[30:33]
	v_mfma_f32_16x16x32_bf16 v[26:29], v[170:173], v[214:217], v[26:29]
	v_mfma_f32_16x16x32_bf16 v[14:17], v[162:165], v[222:225], v[14:17]
	v_mfma_f32_16x16x32_bf16 v[10:13], v[170:173], v[222:225], v[10:13]
	s_setprio 0
	s_setprio 1
	v_mfma_f32_16x16x32_bf16 v[54:57], v[174:177], v[194:197], v[54:57]
	v_mfma_f32_16x16x32_bf16 v[50:53], v[186:189], v[194:197], v[50:53]
	v_mfma_f32_16x16x32_bf16 v[38:41], v[174:177], v[202:205], v[38:41]
	v_mfma_f32_16x16x32_bf16 v[34:37], v[186:189], v[202:205], v[34:37]
	v_mfma_f32_16x16x32_bf16 v[22:25], v[174:177], v[210:213], v[22:25]
	v_mfma_f32_16x16x32_bf16 v[18:21], v[186:189], v[210:213], v[18:21]
	v_mfma_f32_16x16x32_bf16 v[6:9], v[174:177], v[218:221], v[6:9]
	v_mfma_f32_16x16x32_bf16 v[2:5], v[186:189], v[218:221], v[2:5]
	v_mfma_f32_16x16x32_bf16 v[54:57], v[182:185], v[198:201], v[54:57]
	v_mfma_f32_16x16x32_bf16 v[50:53], v[190:193], v[198:201], v[50:53]
	v_mfma_f32_16x16x32_bf16 v[38:41], v[182:185], v[206:209], v[38:41]
	v_mfma_f32_16x16x32_bf16 v[34:37], v[190:193], v[206:209], v[34:37]
	v_mfma_f32_16x16x32_bf16 v[22:25], v[182:185], v[214:217], v[22:25]
	v_mfma_f32_16x16x32_bf16 v[18:21], v[190:193], v[214:217], v[18:21]
	v_mfma_f32_16x16x32_bf16 v[6:9], v[182:185], v[222:225], v[6:9]
	v_mfma_f32_16x16x32_bf16 v[2:5], v[190:193], v[222:225], v[2:5]
	s_setprio 0
	s_barrier
	s_add_i32 s39, s39, 2
	s_add_u32 s12, s12, 0x100
	s_addc_u32 s13, s13, 0
	s_add_u32 s0, s0, 0x100
	s_addc_u32 s1, s1, 0
	s_cmp_gt_u32 s39, 61
	s_cbranch_scc0 .LBB0_341
	s_and_b64 vcc, exec, s[34:35]
	s_cbranch_vccz .LBB0_344
	s_barrier

.LBB0_572:
	s_add_u32 s14, s12, 0xfff00080
	s_addc_u32 s15, s13, -1
	s_add_i32 s30, 0, 0x10000
	s_cmp_eq_u32 s35, 60
	s_cselect_b32 s17, s51, s15
	s_cselect_b32 s16, s50, s14
	v_add_u32_e32 v130, s30, v159
	s_cselect_b32 s15, s53, s1
	s_cselect_b32 s14, s52, s0
	s_add_i32 s42, 0, 0x14000
	s_add_i32 m0, s8, 0xc000
	ds_read_b128 v[152:155], v130
	ds_read_b128 v[162:165], v130 offset:1024
	global_load_lds_dwordx4 v148, s[12:13]
	s_add_i32 m0, s8, 0xe000
	ds_read_b128 v[166:169], v130 offset:2048
	ds_read_b128 v[170:173], v130 offset:3072
	global_load_lds_dwordx4 v150, s[12:13]
	v_add_u32_e32 v130, s42, v159
	ds_read_b128 v[174:177], v130
	ds_read_b128 v[182:185], v130 offset:1024
	ds_read_b128 v[186:189], v130 offset:2048
	ds_read_b128 v[190:193], v130 offset:3072
	ds_read_b128 v[194:197], v161
	ds_read_b128 v[198:201], v161 offset:1024
	ds_read_b128 v[202:205], v161 offset:2048
	ds_read_b128 v[206:209], v161 offset:3072
	ds_read_b128 v[210:213], v161 offset:4096
	ds_read_b128 v[214:217], v161 offset:5120
	ds_read_b128 v[218:221], v161 offset:6144
	ds_read_b128 v[222:225], v161 offset:7168
	s_waitcnt vmcnt(8)
	s_waitcnt lgkmcnt(0)
	s_barrier
	s_setprio 1
	s_waitcnt lgkmcnt(0)
	v_mfma_f32_16x16x32_bf16 v[126:129], v[152:155], v[194:197], v[126:129]
	v_mfma_f32_16x16x32_bf16 v[122:125], v[166:169], v[194:197], v[122:125]
	v_mfma_f32_16x16x32_bf16 v[110:113], v[152:155], v[202:205], v[110:113]
	v_mfma_f32_16x16x32_bf16 v[106:109], v[166:169], v[202:205], v[106:109]
	v_mfma_f32_16x16x32_bf16 v[94:97], v[152:155], v[210:213], v[94:97]
	v_mfma_f32_16x16x32_bf16 v[90:93], v[166:169], v[210:213], v[90:93]
	v_mfma_f32_16x16x32_bf16 v[78:81], v[152:155], v[218:221], v[78:81]
	v_mfma_f32_16x16x32_bf16 v[74:77], v[166:169], v[218:221], v[74:77]
	v_mfma_f32_16x16x32_bf16 v[126:129], v[162:165], v[198:201], v[126:129]
	v_mfma_f32_16x16x32_bf16 v[122:125], v[170:173], v[198:201], v[122:125]
	v_mfma_f32_16x16x32_bf16 v[110:113], v[162:165], v[206:209], v[110:113]
	v_mfma_f32_16x16x32_bf16 v[106:109], v[170:173], v[206:209], v[106:109]
	v_mfma_f32_16x16x32_bf16 v[94:97], v[162:165], v[214:217], v[94:97]
	v_mfma_f32_16x16x32_bf16 v[90:93], v[170:173], v[214:217], v[90:93]
	v_mfma_f32_16x16x32_bf16 v[78:81], v[162:165], v[222:225], v[78:81]
	v_mfma_f32_16x16x32_bf16 v[74:77], v[170:173], v[222:225], v[74:77]
	s_setprio 0
	s_setprio 1
	v_mfma_f32_16x16x32_bf16 v[118:121], v[174:177], v[194:197], v[118:121]
	v_mfma_f32_16x16x32_bf16 v[114:117], v[186:189], v[194:197], v[114:117]
	v_mfma_f32_16x16x32_bf16 v[102:105], v[174:177], v[202:205], v[102:105]
	v_mfma_f32_16x16x32_bf16 v[98:101], v[186:189], v[202:205], v[98:101]
	v_mfma_f32_16x16x32_bf16 v[86:89], v[174:177], v[210:213], v[86:89]
	v_mfma_f32_16x16x32_bf16 v[82:85], v[186:189], v[210:213], v[82:85]
	v_mfma_f32_16x16x32_bf16 v[70:73], v[174:177], v[218:221], v[70:73]
	v_mfma_f32_16x16x32_bf16 v[66:69], v[186:189], v[218:221], v[66:69]
	v_mfma_f32_16x16x32_bf16 v[118:121], v[182:185], v[198:201], v[118:121]
	v_mfma_f32_16x16x32_bf16 v[114:117], v[190:193], v[198:201], v[114:117]
	v_mfma_f32_16x16x32_bf16 v[102:105], v[182:185], v[206:209], v[102:105]
	v_mfma_f32_16x16x32_bf16 v[98:101], v[190:193], v[206:209], v[98:101]
	v_mfma_f32_16x16x32_bf16 v[86:89], v[182:185], v[214:217], v[86:89]
	v_mfma_f32_16x16x32_bf16 v[82:85], v[190:193], v[214:217], v[82:85]
	v_mfma_f32_16x16x32_bf16 v[70:73], v[182:185], v[222:225], v[70:73]
	v_mfma_f32_16x16x32_bf16 v[66:69], v[190:193], v[222:225], v[66:69]
	s_setprio 0
	s_barrier
	s_add_i32 m0, s28, 0x10000
	ds_read_b128 v[194:197], v161 offset:16384
	ds_read_b128 v[198:201], v161 offset:17408
	global_load_lds_dwordx4 v144, s[14:15]
	s_add_i32 m0, s28, 0x12000
	s_add_u32 s98, s14, 0x100000
	s_addc_u32 s99, s15, 0
	ds_read_b128 v[202:205], v161 offset:18432
	global_load_lds_dwordx4 v140, s[14:15]
	s_add_i32 m0, s28, 0x14000
	ds_read_b128 v[206:209], v161 offset:19456
	ds_read_b128 v[210:213], v161 offset:20480
	global_load_lds_dwordx4 v144, s[98:99]
	s_add_i32 m0, s28, 0x16000
	ds_read_b128 v[214:217], v161 offset:21504
	ds_read_b128 v[218:221], v161 offset:22528
	global_load_lds_dwordx4 v140, s[98:99]
	s_mov_b32 m0, s8
	ds_read_b128 v[222:225], v161 offset:23552
	global_load_lds_dwordx4 v146, s[16:17]
	s_mov_b32 m0, s9
	s_nop 0
	global_load_lds_dwordx4 v142, s[16:17]
	s_waitcnt vmcnt(8)
	s_waitcnt lgkmcnt(0)
	s_barrier
	s_setprio 1
	s_waitcnt lgkmcnt(0)
	v_mfma_f32_16x16x32_bf16 v[62:65], v[152:155], v[194:197], v[62:65]
	v_mfma_f32_16x16x32_bf16 v[58:61], v[166:169], v[194:197], v[58:61]
	v_mfma_f32_16x16x32_bf16 v[46:49], v[152:155], v[202:205], v[46:49]
	v_mfma_f32_16x16x32_bf16 v[42:45], v[166:169], v[202:205], v[42:45]
	v_mfma_f32_16x16x32_bf16 v[30:33], v[152:155], v[210:213], v[30:33]
	v_mfma_f32_16x16x32_bf16 v[26:29], v[166:169], v[210:213], v[26:29]
	v_mfma_f32_16x16x32_bf16 v[14:17], v[152:155], v[218:221], v[14:17]
	v_mfma_f32_16x16x32_bf16 v[10:13], v[166:169], v[218:221], v[10:13]
	v_mfma_f32_16x16x32_bf16 v[62:65], v[162:165], v[198:201], v[62:65]
	v_mfma_f32_16x16x32_bf16 v[58:61], v[170:173], v[198:201], v[58:61]
	v_mfma_f32_16x16x32_bf16 v[46:49], v[162:165], v[206:209], v[46:49]
	v_mfma_f32_16x16x32_bf16 v[42:45], v[170:173], v[206:209], v[42:45]
	v_mfma_f32_16x16x32_bf16 v[30:33], v[162:165], v[214:217], v[30:33]
	v_mfma_f32_16x16x32_bf16 v[26:29], v[170:173], v[214:217], v[26:29]
	v_mfma_f32_16x16x32_bf16 v[14:17], v[162:165], v[222:225], v[14:17]
	v_mfma_f32_16x16x32_bf16 v[10:13], v[170:173], v[222:225], v[10:13]
	s_setprio 0
	s_setprio 1
	v_mfma_f32_16x16x32_bf16 v[54:57], v[174:177], v[194:197], v[54:57]
	v_mfma_f32_16x16x32_bf16 v[50:53], v[186:189], v[194:197], v[50:53]
	v_mfma_f32_16x16x32_bf16 v[38:41], v[174:177], v[202:205], v[38:41]
	v_mfma_f32_16x16x32_bf16 v[34:37], v[186:189], v[202:205], v[34:37]
	v_mfma_f32_16x16x32_bf16 v[22:25], v[174:177], v[210:213], v[22:25]
	v_mfma_f32_16x16x32_bf16 v[18:21], v[186:189], v[210:213], v[18:21]
	v_mfma_f32_16x16x32_bf16 v[6:9], v[174:177], v[218:221], v[6:9]
	v_mfma_f32_16x16x32_bf16 v[2:5], v[186:189], v[218:221], v[2:5]
	v_mfma_f32_16x16x32_bf16 v[54:57], v[182:185], v[198:201], v[54:57]
	v_mfma_f32_16x16x32_bf16 v[50:53], v[190:193], v[198:201], v[50:53]
	v_mfma_f32_16x16x32_bf16 v[38:41], v[182:185], v[206:209], v[38:41]
	v_mfma_f32_16x16x32_bf16 v[34:37], v[190:193], v[206:209], v[34:37]
	v_mfma_f32_16x16x32_bf16 v[22:25], v[182:185], v[214:217], v[22:25]
	v_mfma_f32_16x16x32_bf16 v[18:21], v[190:193], v[214:217], v[18:21]
	v_mfma_f32_16x16x32_bf16 v[6:9], v[182:185], v[222:225], v[6:9]
	v_mfma_f32_16x16x32_bf16 v[2:5], v[190:193], v[222:225], v[2:5]
	s_setprio 0
	s_barrier
	s_add_u32 s100, s16, 0x100000
	s_addc_u32 s101, s17, 0
	s_mov_b32 m0, s29
	s_add_i32 s30, 0, 0x18000
	v_add_u32_e32 v130, s30, v159
	s_add_i32 s31, 0, 0x1c000
	ds_read_b128 v[152:155], v130
	ds_read_b128 v[162:165], v130 offset:1024
	global_load_lds_dwordx4 v146, s[100:101]
	s_mov_b32 m0, s36
	ds_read_b128 v[166:169], v130 offset:2048
	ds_read_b128 v[170:173], v130 offset:3072
	global_load_lds_dwordx4 v142, s[100:101]
	v_add_u32_e32 v130, s31, v159
	ds_read_b128 v[174:177], v130
	ds_read_b128 v[182:185], v130 offset:1024
	ds_read_b128 v[186:189], v130 offset:2048
	ds_read_b128 v[190:193], v130 offset:3072
	ds_read_b128 v[194:197], v161 offset:32768
	ds_read_b128 v[198:201], v161 offset:33792
	ds_read_b128 v[202:205], v161 offset:34816
	ds_read_b128 v[206:209], v161 offset:35840
	ds_read_b128 v[210:213], v161 offset:36864
	ds_read_b128 v[214:217], v161 offset:37888
	ds_read_b128 v[218:221], v161 offset:38912
	ds_read_b128 v[222:225], v161 offset:39936
	s_waitcnt vmcnt(8)
	s_waitcnt lgkmcnt(0)
	s_barrier
	s_setprio 1
	s_waitcnt lgkmcnt(0)
	v_mfma_f32_16x16x32_bf16 v[126:129], v[152:155], v[194:197], v[126:129]
	v_mfma_f32_16x16x32_bf16 v[122:125], v[166:169], v[194:197], v[122:125]
	v_mfma_f32_16x16x32_bf16 v[110:113], v[152:155], v[202:205], v[110:113]
	v_mfma_f32_16x16x32_bf16 v[106:109], v[166:169], v[202:205], v[106:109]
	v_mfma_f32_16x16x32_bf16 v[94:97], v[152:155], v[210:213], v[94:97]
	v_mfma_f32_16x16x32_bf16 v[90:93], v[166:169], v[210:213], v[90:93]
	v_mfma_f32_16x16x32_bf16 v[78:81], v[152:155], v[218:221], v[78:81]
	v_mfma_f32_16x16x32_bf16 v[74:77], v[166:169], v[218:221], v[74:77]
	v_mfma_f32_16x16x32_bf16 v[126:129], v[162:165], v[198:201], v[126:129]
	v_mfma_f32_16x16x32_bf16 v[122:125], v[170:173], v[198:201], v[122:125]
	v_mfma_f32_16x16x32_bf16 v[110:113], v[162:165], v[206:209], v[110:113]
	v_mfma_f32_16x16x32_bf16 v[106:109], v[170:173], v[206:209], v[106:109]
	v_mfma_f32_16x16x32_bf16 v[94:97], v[162:165], v[214:217], v[94:97]
	v_mfma_f32_16x16x32_bf16 v[90:93], v[170:173], v[214:217], v[90:93]
	v_mfma_f32_16x16x32_bf16 v[78:81], v[162:165], v[222:225], v[78:81]
	v_mfma_f32_16x16x32_bf16 v[74:77], v[170:173], v[222:225], v[74:77]
	s_setprio 0
	s_setprio 1
	v_mfma_f32_16x16x32_bf16 v[118:121], v[174:177], v[194:197], v[118:121]
	v_mfma_f32_16x16x32_bf16 v[114:117], v[186:189], v[194:197], v[114:117]
	v_mfma_f32_16x16x32_bf16 v[102:105], v[174:177], v[202:205], v[102:105]
	v_mfma_f32_16x16x32_bf16 v[98:101], v[186:189], v[202:205], v[98:101]
	v_mfma_f32_16x16x32_bf16 v[86:89], v[174:177], v[210:213], v[86:89]
	v_mfma_f32_16x16x32_bf16 v[82:85], v[186:189], v[210:213], v[82:85]
	v_mfma_f32_16x16x32_bf16 v[70:73], v[174:177], v[218:221], v[70:73]
	v_mfma_f32_16x16x32_bf16 v[66:69], v[186:189], v[218:221], v[66:69]
	v_mfma_f32_16x16x32_bf16 v[118:121], v[182:185], v[198:201], v[118:121]
	v_mfma_f32_16x16x32_bf16 v[114:117], v[190:193], v[198:201], v[114:117]
	v_mfma_f32_16x16x32_bf16 v[102:105], v[182:185], v[206:209], v[102:105]
	v_mfma_f32_16x16x32_bf16 v[98:101], v[190:193], v[206:209], v[98:101]
	v_mfma_f32_16x16x32_bf16 v[86:89], v[182:185], v[214:217], v[86:89]
	v_mfma_f32_16x16x32_bf16 v[82:85], v[190:193], v[214:217], v[82:85]
	v_mfma_f32_16x16x32_bf16 v[70:73], v[182:185], v[222:225], v[70:73]
	v_mfma_f32_16x16x32_bf16 v[66:69], v[190:193], v[222:225], v[66:69]
	s_setprio 0
	s_barrier
	s_add_u32 s14, s14, 0x80
	s_addc_u32 s15, s15, 0
	s_add_i32 m0, s28, 0x18000
	ds_read_b128 v[194:197], v161 offset:49152
	ds_read_b128 v[198:201], v161 offset:50176
	global_load_lds_dwordx4 v144, s[14:15]
	s_add_i32 m0, s28, 0x1a000
	s_add_u32 s98, s98, 0x80
	s_addc_u32 s99, s99, 0
	ds_read_b128 v[202:205], v161 offset:51200
	global_load_lds_dwordx4 v140, s[14:15]
	s_add_i32 m0, s28, 0x1c000
	ds_read_b128 v[206:209], v161 offset:52224
	ds_read_b128 v[210:213], v161 offset:53248
	global_load_lds_dwordx4 v144, s[98:99]
	s_add_i32 m0, s28, 0x1e000
	s_add_u32 s16, s16, 0x80
	s_addc_u32 s17, s17, 0
	ds_read_b128 v[214:217], v161 offset:54272
	ds_read_b128 v[218:221], v161 offset:55296
	global_load_lds_dwordx4 v140, s[98:99]
	s_mov_b32 m0, s39
	ds_read_b128 v[222:225], v161 offset:56320
	global_load_lds_dwordx4 v146, s[16:17]
	s_mov_b32 m0, s44
	s_nop 0
	global_load_lds_dwordx4 v142, s[16:17]
	s_waitcnt vmcnt(8)
	s_waitcnt lgkmcnt(0)
	s_barrier
	s_setprio 1
	s_waitcnt lgkmcnt(0)
	v_mfma_f32_16x16x32_bf16 v[62:65], v[152:155], v[194:197], v[62:65]
	v_mfma_f32_16x16x32_bf16 v[58:61], v[166:169], v[194:197], v[58:61]
	v_mfma_f32_16x16x32_bf16 v[46:49], v[152:155], v[202:205], v[46:49]
	v_mfma_f32_16x16x32_bf16 v[42:45], v[166:169], v[202:205], v[42:45]
	v_mfma_f32_16x16x32_bf16 v[30:33], v[152:155], v[210:213], v[30:33]
	v_mfma_f32_16x16x32_bf16 v[26:29], v[166:169], v[210:213], v[26:29]
	v_mfma_f32_16x16x32_bf16 v[14:17], v[152:155], v[218:221], v[14:17]
	v_mfma_f32_16x16x32_bf16 v[10:13], v[166:169], v[218:221], v[10:13]
	v_mfma_f32_16x16x32_bf16 v[62:65], v[162:165], v[198:201], v[62:65]
	v_mfma_f32_16x16x32_bf16 v[58:61], v[170:173], v[198:201], v[58:61]
	v_mfma_f32_16x16x32_bf16 v[46:49], v[162:165], v[206:209], v[46:49]
	v_mfma_f32_16x16x32_bf16 v[42:45], v[170:173], v[206:209], v[42:45]
	v_mfma_f32_16x16x32_bf16 v[30:33], v[162:165], v[214:217], v[30:33]
	v_mfma_f32_16x16x32_bf16 v[26:29], v[170:173], v[214:217], v[26:29]
	v_mfma_f32_16x16x32_bf16 v[14:17], v[162:165], v[222:225], v[14:17]
	v_mfma_f32_16x16x32_bf16 v[10:13], v[170:173], v[222:225], v[10:13]
	s_setprio 0
	s_setprio 1
	v_mfma_f32_16x16x32_bf16 v[54:57], v[174:177], v[194:197], v[54:57]
	v_mfma_f32_16x16x32_bf16 v[50:53], v[186:189], v[194:197], v[50:53]
	v_mfma_f32_16x16x32_bf16 v[38:41], v[174:177], v[202:205], v[38:41]
	v_mfma_f32_16x16x32_bf16 v[34:37], v[186:189], v[202:205], v[34:37]
	v_mfma_f32_16x16x32_bf16 v[22:25], v[174:177], v[210:213], v[22:25]
	v_mfma_f32_16x16x32_bf16 v[18:21], v[186:189], v[210:213], v[18:21]
	v_mfma_f32_16x16x32_bf16 v[6:9], v[174:177], v[218:221], v[6:9]
	v_mfma_f32_16x16x32_bf16 v[2:5], v[186:189], v[218:221], v[2:5]
	v_mfma_f32_16x16x32_bf16 v[54:57], v[182:185], v[198:201], v[54:57]
	v_mfma_f32_16x16x32_bf16 v[50:53], v[190:193], v[198:201], v[50:53]
	v_mfma_f32_16x16x32_bf16 v[38:41], v[182:185], v[206:209], v[38:41]
	v_mfma_f32_16x16x32_bf16 v[34:37], v[190:193], v[206:209], v[34:37]
	v_mfma_f32_16x16x32_bf16 v[22:25], v[182:185], v[214:217], v[22:25]
	v_mfma_f32_16x16x32_bf16 v[18:21], v[190:193], v[214:217], v[18:21]
	v_mfma_f32_16x16x32_bf16 v[6:9], v[182:185], v[222:225], v[6:9]
	v_mfma_f32_16x16x32_bf16 v[2:5], v[190:193], v[222:225], v[2:5]
	s_setprio 0
	s_barrier
	s_add_i32 s35, s35, 2
	s_add_u32 s12, s12, 0x100
	s_addc_u32 s13, s13, 0
	s_add_u32 s0, s0, 0x100
	s_addc_u32 s1, s1, 0
	s_cmp_gt_u32 s35, 61
	s_cbranch_scc0 .LBB0_572
	s_and_b64 vcc, exec, s[10:11]
	s_cbranch_vccz .LBB0_575
	s_barrier

.LBB0_882:
	s_add_u32 s20, s10, 0xfff00080
	s_addc_u32 s21, s11, -1
	s_add_i32 s22, 0, 0x10000
	s_cmp_eq_u32 s12, 60
	s_cselect_b32 s43, s55, s21
	s_cselect_b32 s42, s54, s20
	v_add_u32_e32 v2, s22, v155
	s_cselect_b32 s39, s37, s1
	s_cselect_b32 s38, s36, s0
	s_add_i32 s23, 0, 0x14000
	s_add_i32 m0, s29, 0xc000
	ds_read_b128 v[146:149], v2
	ds_read_b128 v[150:153], v2 offset:1024
	global_load_lds_dwordx4 v140, s[10:11]
	s_add_i32 m0, s29, 0xe000
	ds_read_b128 v[158:161], v2 offset:2048
	ds_read_b128 v[162:165], v2 offset:3072
	global_load_lds_dwordx4 v142, s[10:11]
	v_add_u32_e32 v2, s23, v155
	ds_read_b128 v[166:169], v2
	ds_read_b128 v[170:173], v2 offset:1024
	ds_read_b128 v[174:177], v2 offset:2048
	ds_read_b128 v[186:189], v2 offset:3072
	ds_read_b128 v[190:193], v157
	ds_read_b128 v[194:197], v157 offset:1024
	ds_read_b128 v[198:201], v157 offset:2048
	ds_read_b128 v[202:205], v157 offset:3072
	ds_read_b128 v[206:209], v157 offset:4096
	ds_read_b128 v[210:213], v157 offset:5120
	ds_read_b128 v[214:217], v157 offset:6144
	ds_read_b128 v[218:221], v157 offset:7168
	s_waitcnt vmcnt(8)
	s_waitcnt lgkmcnt(0)
	s_barrier
	s_setprio 1
	s_waitcnt lgkmcnt(0)
	v_mfma_f32_16x16x32_bf16 v[128:131], v[146:149], v[190:193], v[128:131]
	v_mfma_f32_16x16x32_bf16 v[124:127], v[158:161], v[190:193], v[124:127]
	v_mfma_f32_16x16x32_bf16 v[112:115], v[146:149], v[198:201], v[112:115]
	v_mfma_f32_16x16x32_bf16 v[108:111], v[158:161], v[198:201], v[108:111]
	v_mfma_f32_16x16x32_bf16 v[96:99], v[146:149], v[206:209], v[96:99]
	v_mfma_f32_16x16x32_bf16 v[92:95], v[158:161], v[206:209], v[92:95]
	v_mfma_f32_16x16x32_bf16 v[80:83], v[146:149], v[214:217], v[80:83]
	v_mfma_f32_16x16x32_bf16 v[76:79], v[158:161], v[214:217], v[76:79]
	v_mfma_f32_16x16x32_bf16 v[128:131], v[150:153], v[194:197], v[128:131]
	v_mfma_f32_16x16x32_bf16 v[124:127], v[162:165], v[194:197], v[124:127]
	v_mfma_f32_16x16x32_bf16 v[112:115], v[150:153], v[202:205], v[112:115]
	v_mfma_f32_16x16x32_bf16 v[108:111], v[162:165], v[202:205], v[108:111]
	v_mfma_f32_16x16x32_bf16 v[96:99], v[150:153], v[210:213], v[96:99]
	v_mfma_f32_16x16x32_bf16 v[92:95], v[162:165], v[210:213], v[92:95]
	v_mfma_f32_16x16x32_bf16 v[80:83], v[150:153], v[218:221], v[80:83]
	v_mfma_f32_16x16x32_bf16 v[76:79], v[162:165], v[218:221], v[76:79]
	s_setprio 0
	s_setprio 1
	v_mfma_f32_16x16x32_bf16 v[120:123], v[166:169], v[190:193], v[120:123]
	v_mfma_f32_16x16x32_bf16 v[116:119], v[174:177], v[190:193], v[116:119]
	v_mfma_f32_16x16x32_bf16 v[104:107], v[166:169], v[198:201], v[104:107]
	v_mfma_f32_16x16x32_bf16 v[100:103], v[174:177], v[198:201], v[100:103]
	v_mfma_f32_16x16x32_bf16 v[88:91], v[166:169], v[206:209], v[88:91]
	v_mfma_f32_16x16x32_bf16 v[84:87], v[174:177], v[206:209], v[84:87]
	v_mfma_f32_16x16x32_bf16 v[72:75], v[166:169], v[214:217], v[72:75]
	v_mfma_f32_16x16x32_bf16 v[68:71], v[174:177], v[214:217], v[68:71]
	v_mfma_f32_16x16x32_bf16 v[120:123], v[170:173], v[194:197], v[120:123]
	v_mfma_f32_16x16x32_bf16 v[116:119], v[186:189], v[194:197], v[116:119]
	v_mfma_f32_16x16x32_bf16 v[104:107], v[170:173], v[202:205], v[104:107]
	v_mfma_f32_16x16x32_bf16 v[100:103], v[186:189], v[202:205], v[100:103]
	v_mfma_f32_16x16x32_bf16 v[88:91], v[170:173], v[210:213], v[88:91]
	v_mfma_f32_16x16x32_bf16 v[84:87], v[186:189], v[210:213], v[84:87]
	v_mfma_f32_16x16x32_bf16 v[72:75], v[170:173], v[218:221], v[72:75]
	v_mfma_f32_16x16x32_bf16 v[68:71], v[186:189], v[218:221], v[68:71]
	s_setprio 0
	s_barrier
	s_add_i32 m0, s58, 0x10000
	ds_read_b128 v[190:193], v157 offset:16384
	ds_read_b128 v[194:197], v157 offset:17408
	global_load_lds_dwordx4 v134, s[38:39]
	s_add_i32 m0, s58, 0x12000
	s_add_u32 s98, s38, 0x100000
	s_addc_u32 s99, s39, 0
	ds_read_b128 v[198:201], v157 offset:18432
	global_load_lds_dwordx4 v138, s[38:39]
	s_add_i32 m0, s58, 0x14000
	ds_read_b128 v[202:205], v157 offset:19456
	ds_read_b128 v[206:209], v157 offset:20480
	global_load_lds_dwordx4 v134, s[98:99]
	s_add_i32 m0, s58, 0x16000
	ds_read_b128 v[210:213], v157 offset:21504
	ds_read_b128 v[214:217], v157 offset:22528
	global_load_lds_dwordx4 v138, s[98:99]
	s_mov_b32 m0, s29
	ds_read_b128 v[218:221], v157 offset:23552
	global_load_lds_dwordx4 v132, s[42:43]
	s_mov_b32 m0, s31
	s_nop 0
	global_load_lds_dwordx4 v136, s[42:43]
	s_waitcnt vmcnt(8)
	s_waitcnt lgkmcnt(0)
	s_barrier
	s_setprio 1
	s_waitcnt lgkmcnt(0)
	v_mfma_f32_16x16x32_bf16 v[64:67], v[146:149], v[190:193], v[64:67]
	v_mfma_f32_16x16x32_bf16 v[60:63], v[158:161], v[190:193], v[60:63]
	v_mfma_f32_16x16x32_bf16 v[48:51], v[146:149], v[198:201], v[48:51]
	v_mfma_f32_16x16x32_bf16 v[44:47], v[158:161], v[198:201], v[44:47]
	v_mfma_f32_16x16x32_bf16 v[32:35], v[146:149], v[206:209], v[32:35]
	v_mfma_f32_16x16x32_bf16 v[28:31], v[158:161], v[206:209], v[28:31]
	v_mfma_f32_16x16x32_bf16 v[16:19], v[146:149], v[214:217], v[16:19]
	v_mfma_f32_16x16x32_bf16 v[12:15], v[158:161], v[214:217], v[12:15]
	v_mfma_f32_16x16x32_bf16 v[64:67], v[150:153], v[194:197], v[64:67]
	v_mfma_f32_16x16x32_bf16 v[60:63], v[162:165], v[194:197], v[60:63]
	v_mfma_f32_16x16x32_bf16 v[48:51], v[150:153], v[202:205], v[48:51]
	v_mfma_f32_16x16x32_bf16 v[44:47], v[162:165], v[202:205], v[44:47]
	v_mfma_f32_16x16x32_bf16 v[32:35], v[150:153], v[210:213], v[32:35]
	v_mfma_f32_16x16x32_bf16 v[28:31], v[162:165], v[210:213], v[28:31]
	v_mfma_f32_16x16x32_bf16 v[16:19], v[150:153], v[218:221], v[16:19]
	v_mfma_f32_16x16x32_bf16 v[12:15], v[162:165], v[218:221], v[12:15]
	s_setprio 0
	s_setprio 1
	v_mfma_f32_16x16x32_bf16 v[56:59], v[166:169], v[190:193], v[56:59]
	v_mfma_f32_16x16x32_bf16 v[52:55], v[174:177], v[190:193], v[52:55]
	v_mfma_f32_16x16x32_bf16 v[40:43], v[166:169], v[198:201], v[40:43]
	v_mfma_f32_16x16x32_bf16 v[36:39], v[174:177], v[198:201], v[36:39]
	v_mfma_f32_16x16x32_bf16 v[24:27], v[166:169], v[206:209], v[24:27]
	v_mfma_f32_16x16x32_bf16 v[20:23], v[174:177], v[206:209], v[20:23]
	v_mfma_f32_16x16x32_bf16 v[8:11], v[166:169], v[214:217], v[8:11]
	v_mfma_f32_16x16x32_bf16 v[4:7], v[174:177], v[214:217], v[4:7]
	v_mfma_f32_16x16x32_bf16 v[56:59], v[170:173], v[194:197], v[56:59]
	v_mfma_f32_16x16x32_bf16 v[52:55], v[186:189], v[194:197], v[52:55]
	v_mfma_f32_16x16x32_bf16 v[40:43], v[170:173], v[202:205], v[40:43]
	v_mfma_f32_16x16x32_bf16 v[36:39], v[186:189], v[202:205], v[36:39]
	v_mfma_f32_16x16x32_bf16 v[24:27], v[170:173], v[210:213], v[24:27]
	v_mfma_f32_16x16x32_bf16 v[20:23], v[186:189], v[210:213], v[20:23]
	v_mfma_f32_16x16x32_bf16 v[8:11], v[170:173], v[218:221], v[8:11]
	v_mfma_f32_16x16x32_bf16 v[4:7], v[186:189], v[218:221], v[4:7]
	s_setprio 0
	s_barrier
	s_add_u32 s100, s42, 0x100000
	s_addc_u32 s101, s43, 0
	s_mov_b32 m0, s59
	s_add_i32 s22, 0, 0x18000
	v_add_u32_e32 v2, s22, v155
	s_add_i32 s23, 0, 0x1c000
	ds_read_b128 v[146:149], v2
	ds_read_b128 v[150:153], v2 offset:1024
	global_load_lds_dwordx4 v132, s[100:101]
	s_mov_b32 m0, s94
	ds_read_b128 v[158:161], v2 offset:2048
	ds_read_b128 v[162:165], v2 offset:3072
	global_load_lds_dwordx4 v136, s[100:101]
	v_add_u32_e32 v2, s23, v155
	ds_read_b128 v[166:169], v2
	ds_read_b128 v[170:173], v2 offset:1024
	ds_read_b128 v[174:177], v2 offset:2048
	ds_read_b128 v[186:189], v2 offset:3072
	ds_read_b128 v[190:193], v157 offset:32768
	ds_read_b128 v[194:197], v157 offset:33792
	ds_read_b128 v[198:201], v157 offset:34816
	ds_read_b128 v[202:205], v157 offset:35840
	ds_read_b128 v[206:209], v157 offset:36864
	ds_read_b128 v[210:213], v157 offset:37888
	ds_read_b128 v[214:217], v157 offset:38912
	ds_read_b128 v[218:221], v157 offset:39936
	s_waitcnt vmcnt(8)
	s_waitcnt lgkmcnt(0)
	s_barrier
	s_setprio 1
	s_waitcnt lgkmcnt(0)
	v_mfma_f32_16x16x32_bf16 v[128:131], v[146:149], v[190:193], v[128:131]
	v_mfma_f32_16x16x32_bf16 v[124:127], v[158:161], v[190:193], v[124:127]
	v_mfma_f32_16x16x32_bf16 v[112:115], v[146:149], v[198:201], v[112:115]
	v_mfma_f32_16x16x32_bf16 v[108:111], v[158:161], v[198:201], v[108:111]
	v_mfma_f32_16x16x32_bf16 v[96:99], v[146:149], v[206:209], v[96:99]
	v_mfma_f32_16x16x32_bf16 v[92:95], v[158:161], v[206:209], v[92:95]
	v_mfma_f32_16x16x32_bf16 v[80:83], v[146:149], v[214:217], v[80:83]
	v_mfma_f32_16x16x32_bf16 v[76:79], v[158:161], v[214:217], v[76:79]
	v_mfma_f32_16x16x32_bf16 v[128:131], v[150:153], v[194:197], v[128:131]
	v_mfma_f32_16x16x32_bf16 v[124:127], v[162:165], v[194:197], v[124:127]
	v_mfma_f32_16x16x32_bf16 v[112:115], v[150:153], v[202:205], v[112:115]
	v_mfma_f32_16x16x32_bf16 v[108:111], v[162:165], v[202:205], v[108:111]
	v_mfma_f32_16x16x32_bf16 v[96:99], v[150:153], v[210:213], v[96:99]
	v_mfma_f32_16x16x32_bf16 v[92:95], v[162:165], v[210:213], v[92:95]
	v_mfma_f32_16x16x32_bf16 v[80:83], v[150:153], v[218:221], v[80:83]
	v_mfma_f32_16x16x32_bf16 v[76:79], v[162:165], v[218:221], v[76:79]
	s_setprio 0
	s_setprio 1
	v_mfma_f32_16x16x32_bf16 v[120:123], v[166:169], v[190:193], v[120:123]
	v_mfma_f32_16x16x32_bf16 v[116:119], v[174:177], v[190:193], v[116:119]
	v_mfma_f32_16x16x32_bf16 v[104:107], v[166:169], v[198:201], v[104:107]
	v_mfma_f32_16x16x32_bf16 v[100:103], v[174:177], v[198:201], v[100:103]
	v_mfma_f32_16x16x32_bf16 v[88:91], v[166:169], v[206:209], v[88:91]
	v_mfma_f32_16x16x32_bf16 v[84:87], v[174:177], v[206:209], v[84:87]
	v_mfma_f32_16x16x32_bf16 v[72:75], v[166:169], v[214:217], v[72:75]
	v_mfma_f32_16x16x32_bf16 v[68:71], v[174:177], v[214:217], v[68:71]
	v_mfma_f32_16x16x32_bf16 v[120:123], v[170:173], v[194:197], v[120:123]
	v_mfma_f32_16x16x32_bf16 v[116:119], v[186:189], v[194:197], v[116:119]
	v_mfma_f32_16x16x32_bf16 v[104:107], v[170:173], v[202:205], v[104:107]
	v_mfma_f32_16x16x32_bf16 v[100:103], v[186:189], v[202:205], v[100:103]
	v_mfma_f32_16x16x32_bf16 v[88:91], v[170:173], v[210:213], v[88:91]
	v_mfma_f32_16x16x32_bf16 v[84:87], v[186:189], v[210:213], v[84:87]
	v_mfma_f32_16x16x32_bf16 v[72:75], v[170:173], v[218:221], v[72:75]
	v_mfma_f32_16x16x32_bf16 v[68:71], v[186:189], v[218:221], v[68:71]
	s_setprio 0
	s_barrier
	s_add_u32 s38, s38, 0x80
	s_addc_u32 s39, s39, 0
	s_add_i32 m0, s58, 0x18000
	ds_read_b128 v[190:193], v157 offset:49152
	ds_read_b128 v[194:197], v157 offset:50176
	global_load_lds_dwordx4 v134, s[38:39]
	s_add_i32 m0, s58, 0x1a000
	s_add_u32 s98, s98, 0x80
	s_addc_u32 s99, s99, 0
	ds_read_b128 v[198:201], v157 offset:51200
	global_load_lds_dwordx4 v138, s[38:39]
	s_add_i32 m0, s58, 0x1c000
	ds_read_b128 v[202:205], v157 offset:52224
	ds_read_b128 v[206:209], v157 offset:53248
	global_load_lds_dwordx4 v134, s[98:99]
	s_add_i32 m0, s58, 0x1e000
	s_add_u32 s42, s42, 0x80
	s_addc_u32 s43, s43, 0
	ds_read_b128 v[210:213], v157 offset:54272
	ds_read_b128 v[214:217], v157 offset:55296
	global_load_lds_dwordx4 v138, s[98:99]
	s_mov_b32 m0, s14
	ds_read_b128 v[218:221], v157 offset:56320
	global_load_lds_dwordx4 v132, s[42:43]
	s_mov_b32 m0, s15
	s_nop 0
	global_load_lds_dwordx4 v136, s[42:43]
	s_waitcnt vmcnt(8)
	s_waitcnt lgkmcnt(0)
	s_barrier
	s_setprio 1
	s_waitcnt lgkmcnt(0)
	v_mfma_f32_16x16x32_bf16 v[64:67], v[146:149], v[190:193], v[64:67]
	v_mfma_f32_16x16x32_bf16 v[60:63], v[158:161], v[190:193], v[60:63]
	v_mfma_f32_16x16x32_bf16 v[48:51], v[146:149], v[198:201], v[48:51]
	v_mfma_f32_16x16x32_bf16 v[44:47], v[158:161], v[198:201], v[44:47]
	v_mfma_f32_16x16x32_bf16 v[32:35], v[146:149], v[206:209], v[32:35]
	v_mfma_f32_16x16x32_bf16 v[28:31], v[158:161], v[206:209], v[28:31]
	v_mfma_f32_16x16x32_bf16 v[16:19], v[146:149], v[214:217], v[16:19]
	v_mfma_f32_16x16x32_bf16 v[12:15], v[158:161], v[214:217], v[12:15]
	v_mfma_f32_16x16x32_bf16 v[64:67], v[150:153], v[194:197], v[64:67]
	v_mfma_f32_16x16x32_bf16 v[60:63], v[162:165], v[194:197], v[60:63]
	v_mfma_f32_16x16x32_bf16 v[48:51], v[150:153], v[202:205], v[48:51]
	v_mfma_f32_16x16x32_bf16 v[44:47], v[162:165], v[202:205], v[44:47]
	v_mfma_f32_16x16x32_bf16 v[32:35], v[150:153], v[210:213], v[32:35]
	v_mfma_f32_16x16x32_bf16 v[28:31], v[162:165], v[210:213], v[28:31]
	v_mfma_f32_16x16x32_bf16 v[16:19], v[150:153], v[218:221], v[16:19]
	v_mfma_f32_16x16x32_bf16 v[12:15], v[162:165], v[218:221], v[12:15]
	s_setprio 0
	s_setprio 1
	v_mfma_f32_16x16x32_bf16 v[56:59], v[166:169], v[190:193], v[56:59]
	v_mfma_f32_16x16x32_bf16 v[52:55], v[174:177], v[190:193], v[52:55]
	v_mfma_f32_16x16x32_bf16 v[40:43], v[166:169], v[198:201], v[40:43]
	v_mfma_f32_16x16x32_bf16 v[36:39], v[174:177], v[198:201], v[36:39]
	v_mfma_f32_16x16x32_bf16 v[24:27], v[166:169], v[206:209], v[24:27]
	v_mfma_f32_16x16x32_bf16 v[20:23], v[174:177], v[206:209], v[20:23]
	v_mfma_f32_16x16x32_bf16 v[8:11], v[166:169], v[214:217], v[8:11]
	v_mfma_f32_16x16x32_bf16 v[4:7], v[174:177], v[214:217], v[4:7]
	v_mfma_f32_16x16x32_bf16 v[56:59], v[170:173], v[194:197], v[56:59]
	v_mfma_f32_16x16x32_bf16 v[52:55], v[186:189], v[194:197], v[52:55]
	v_mfma_f32_16x16x32_bf16 v[40:43], v[170:173], v[202:205], v[40:43]
	v_mfma_f32_16x16x32_bf16 v[36:39], v[186:189], v[202:205], v[36:39]
	v_mfma_f32_16x16x32_bf16 v[24:27], v[170:173], v[210:213], v[24:27]
	v_mfma_f32_16x16x32_bf16 v[20:23], v[186:189], v[210:213], v[20:23]
	v_mfma_f32_16x16x32_bf16 v[8:11], v[170:173], v[218:221], v[8:11]
	v_mfma_f32_16x16x32_bf16 v[4:7], v[186:189], v[218:221], v[4:7]
	s_setprio 0
	s_barrier
	s_add_i32 s12, s12, 2
	s_add_u32 s10, s10, 0x100
	s_addc_u32 s11, s11, 0
	s_add_u32 s0, s0, 0x100
	s_addc_u32 s1, s1, 0
	s_cmp_gt_u32 s12, 61
	s_cbranch_scc0 .LBB0_882
	s_and_b64 vcc, exec, s[48:49]
	s_cbranch_vccz .LBB0_885
	s_barrier

.LBB0_1226:
	s_add_u32 s21, s10, 0xfff00080
	s_addc_u32 s22, s11, -1
	s_add_i32 s23, 0, 0x10000
	s_cmp_eq_u32 s20, 60
	s_cselect_b32 s31, s53, s22
	s_cselect_b32 s30, s52, s21
	v_add_u32_e32 v2, s23, v151
	s_cselect_b32 s29, s55, s1
	s_cselect_b32 s28, s54, s0
	s_add_i32 s21, 0, 0x14000
	s_add_i32 m0, s8, 0xc000
	ds_read_b128 v[144:147], v2
	ds_read_b128 v[154:157], v2 offset:1024
	global_load_lds_dwordx4 v140, s[10:11]
	s_add_i32 m0, s8, 0xe000
	ds_read_b128 v[158:161], v2 offset:2048
	ds_read_b128 v[162:165], v2 offset:3072
	global_load_lds_dwordx4 v142, s[10:11]
	v_add_u32_e32 v2, s21, v151
	ds_read_b128 v[166:169], v2
	ds_read_b128 v[170:173], v2 offset:1024
	ds_read_b128 v[174:177], v2 offset:2048
	ds_read_b128 v[186:189], v2 offset:3072
	ds_read_b128 v[190:193], v153
	ds_read_b128 v[194:197], v153 offset:1024
	ds_read_b128 v[198:201], v153 offset:2048
	ds_read_b128 v[202:205], v153 offset:3072
	ds_read_b128 v[206:209], v153 offset:4096
	ds_read_b128 v[210:213], v153 offset:5120
	ds_read_b128 v[214:217], v153 offset:6144
	ds_read_b128 v[218:221], v153 offset:7168
	s_waitcnt vmcnt(8)
	s_waitcnt lgkmcnt(0)
	s_barrier
	s_setprio 1
	s_waitcnt lgkmcnt(0)
	v_mfma_f32_16x16x32_bf16 v[128:131], v[144:147], v[190:193], v[128:131]
	v_mfma_f32_16x16x32_bf16 v[124:127], v[158:161], v[190:193], v[124:127]
	v_mfma_f32_16x16x32_bf16 v[112:115], v[144:147], v[198:201], v[112:115]
	v_mfma_f32_16x16x32_bf16 v[108:111], v[158:161], v[198:201], v[108:111]
	v_mfma_f32_16x16x32_bf16 v[96:99], v[144:147], v[206:209], v[96:99]
	v_mfma_f32_16x16x32_bf16 v[92:95], v[158:161], v[206:209], v[92:95]
	v_mfma_f32_16x16x32_bf16 v[80:83], v[144:147], v[214:217], v[80:83]
	v_mfma_f32_16x16x32_bf16 v[76:79], v[158:161], v[214:217], v[76:79]
	v_mfma_f32_16x16x32_bf16 v[128:131], v[154:157], v[194:197], v[128:131]
	v_mfma_f32_16x16x32_bf16 v[124:127], v[162:165], v[194:197], v[124:127]
	v_mfma_f32_16x16x32_bf16 v[112:115], v[154:157], v[202:205], v[112:115]
	v_mfma_f32_16x16x32_bf16 v[108:111], v[162:165], v[202:205], v[108:111]
	v_mfma_f32_16x16x32_bf16 v[96:99], v[154:157], v[210:213], v[96:99]
	v_mfma_f32_16x16x32_bf16 v[92:95], v[162:165], v[210:213], v[92:95]
	v_mfma_f32_16x16x32_bf16 v[80:83], v[154:157], v[218:221], v[80:83]
	v_mfma_f32_16x16x32_bf16 v[76:79], v[162:165], v[218:221], v[76:79]
	s_setprio 0
	s_setprio 1
	v_mfma_f32_16x16x32_bf16 v[120:123], v[166:169], v[190:193], v[120:123]
	v_mfma_f32_16x16x32_bf16 v[116:119], v[174:177], v[190:193], v[116:119]
	v_mfma_f32_16x16x32_bf16 v[104:107], v[166:169], v[198:201], v[104:107]
	v_mfma_f32_16x16x32_bf16 v[100:103], v[174:177], v[198:201], v[100:103]
	v_mfma_f32_16x16x32_bf16 v[88:91], v[166:169], v[206:209], v[88:91]
	v_mfma_f32_16x16x32_bf16 v[84:87], v[174:177], v[206:209], v[84:87]
	v_mfma_f32_16x16x32_bf16 v[72:75], v[166:169], v[214:217], v[72:75]
	v_mfma_f32_16x16x32_bf16 v[68:71], v[174:177], v[214:217], v[68:71]
	v_mfma_f32_16x16x32_bf16 v[120:123], v[170:173], v[194:197], v[120:123]
	v_mfma_f32_16x16x32_bf16 v[116:119], v[186:189], v[194:197], v[116:119]
	v_mfma_f32_16x16x32_bf16 v[104:107], v[170:173], v[202:205], v[104:107]
	v_mfma_f32_16x16x32_bf16 v[100:103], v[186:189], v[202:205], v[100:103]
	v_mfma_f32_16x16x32_bf16 v[88:91], v[170:173], v[210:213], v[88:91]
	v_mfma_f32_16x16x32_bf16 v[84:87], v[186:189], v[210:213], v[84:87]
	v_mfma_f32_16x16x32_bf16 v[72:75], v[170:173], v[218:221], v[72:75]
	v_mfma_f32_16x16x32_bf16 v[68:71], v[186:189], v[218:221], v[68:71]
	s_setprio 0
	s_barrier
	s_add_i32 m0, s38, 0x10000
	ds_read_b128 v[190:193], v153 offset:16384
	ds_read_b128 v[194:197], v153 offset:17408
	global_load_lds_dwordx4 v136, s[28:29]
	s_add_i32 m0, s38, 0x12000
	s_add_u32 s98, s28, 0x100000
	s_addc_u32 s99, s29, 0
	ds_read_b128 v[198:201], v153 offset:18432
	global_load_lds_dwordx4 v132, s[28:29]
	s_add_i32 m0, s38, 0x14000
	ds_read_b128 v[202:205], v153 offset:19456
	ds_read_b128 v[206:209], v153 offset:20480
	global_load_lds_dwordx4 v136, s[98:99]
	s_add_i32 m0, s38, 0x16000
	ds_read_b128 v[210:213], v153 offset:21504
	ds_read_b128 v[214:217], v153 offset:22528
	global_load_lds_dwordx4 v132, s[98:99]
	s_mov_b32 m0, s8
	ds_read_b128 v[218:221], v153 offset:23552
	global_load_lds_dwordx4 v138, s[30:31]
	s_mov_b32 m0, s9
	s_nop 0
	global_load_lds_dwordx4 v134, s[30:31]
	s_waitcnt vmcnt(8)
	s_waitcnt lgkmcnt(0)
	s_barrier
	s_setprio 1
	s_waitcnt lgkmcnt(0)
	v_mfma_f32_16x16x32_bf16 v[64:67], v[144:147], v[190:193], v[64:67]
	v_mfma_f32_16x16x32_bf16 v[60:63], v[158:161], v[190:193], v[60:63]
	v_mfma_f32_16x16x32_bf16 v[48:51], v[144:147], v[198:201], v[48:51]
	v_mfma_f32_16x16x32_bf16 v[44:47], v[158:161], v[198:201], v[44:47]
	v_mfma_f32_16x16x32_bf16 v[32:35], v[144:147], v[206:209], v[32:35]
	v_mfma_f32_16x16x32_bf16 v[28:31], v[158:161], v[206:209], v[28:31]
	v_mfma_f32_16x16x32_bf16 v[16:19], v[144:147], v[214:217], v[16:19]
	v_mfma_f32_16x16x32_bf16 v[12:15], v[158:161], v[214:217], v[12:15]
	v_mfma_f32_16x16x32_bf16 v[64:67], v[154:157], v[194:197], v[64:67]
	v_mfma_f32_16x16x32_bf16 v[60:63], v[162:165], v[194:197], v[60:63]
	v_mfma_f32_16x16x32_bf16 v[48:51], v[154:157], v[202:205], v[48:51]
	v_mfma_f32_16x16x32_bf16 v[44:47], v[162:165], v[202:205], v[44:47]
	v_mfma_f32_16x16x32_bf16 v[32:35], v[154:157], v[210:213], v[32:35]
	v_mfma_f32_16x16x32_bf16 v[28:31], v[162:165], v[210:213], v[28:31]
	v_mfma_f32_16x16x32_bf16 v[16:19], v[154:157], v[218:221], v[16:19]
	v_mfma_f32_16x16x32_bf16 v[12:15], v[162:165], v[218:221], v[12:15]
	s_setprio 0
	s_setprio 1
	v_mfma_f32_16x16x32_bf16 v[56:59], v[166:169], v[190:193], v[56:59]
	v_mfma_f32_16x16x32_bf16 v[52:55], v[174:177], v[190:193], v[52:55]
	v_mfma_f32_16x16x32_bf16 v[40:43], v[166:169], v[198:201], v[40:43]
	v_mfma_f32_16x16x32_bf16 v[36:39], v[174:177], v[198:201], v[36:39]
	v_mfma_f32_16x16x32_bf16 v[24:27], v[166:169], v[206:209], v[24:27]
	v_mfma_f32_16x16x32_bf16 v[20:23], v[174:177], v[206:209], v[20:23]
	v_mfma_f32_16x16x32_bf16 v[8:11], v[166:169], v[214:217], v[8:11]
	v_mfma_f32_16x16x32_bf16 v[4:7], v[174:177], v[214:217], v[4:7]
	v_mfma_f32_16x16x32_bf16 v[56:59], v[170:173], v[194:197], v[56:59]
	v_mfma_f32_16x16x32_bf16 v[52:55], v[186:189], v[194:197], v[52:55]
	v_mfma_f32_16x16x32_bf16 v[40:43], v[170:173], v[202:205], v[40:43]
	v_mfma_f32_16x16x32_bf16 v[36:39], v[186:189], v[202:205], v[36:39]
	v_mfma_f32_16x16x32_bf16 v[24:27], v[170:173], v[210:213], v[24:27]
	v_mfma_f32_16x16x32_bf16 v[20:23], v[186:189], v[210:213], v[20:23]
	v_mfma_f32_16x16x32_bf16 v[8:11], v[170:173], v[218:221], v[8:11]
	v_mfma_f32_16x16x32_bf16 v[4:7], v[186:189], v[218:221], v[4:7]
	s_setprio 0
	s_barrier
	s_add_u32 s100, s30, 0x100000
	s_addc_u32 s101, s31, 0
	s_mov_b32 m0, s16
	s_add_i32 s21, 0, 0x18000
	v_add_u32_e32 v2, s21, v151
	s_add_i32 s24, 0, 0x1c000
	ds_read_b128 v[144:147], v2
	ds_read_b128 v[154:157], v2 offset:1024
	global_load_lds_dwordx4 v138, s[100:101]
	s_mov_b32 m0, s17
	ds_read_b128 v[158:161], v2 offset:2048
	ds_read_b128 v[162:165], v2 offset:3072
	global_load_lds_dwordx4 v134, s[100:101]
	v_add_u32_e32 v2, s24, v151
	ds_read_b128 v[166:169], v2
	ds_read_b128 v[170:173], v2 offset:1024
	ds_read_b128 v[174:177], v2 offset:2048
	ds_read_b128 v[186:189], v2 offset:3072
	ds_read_b128 v[190:193], v153 offset:32768
	ds_read_b128 v[194:197], v153 offset:33792
	ds_read_b128 v[198:201], v153 offset:34816
	ds_read_b128 v[202:205], v153 offset:35840
	ds_read_b128 v[206:209], v153 offset:36864
	ds_read_b128 v[210:213], v153 offset:37888
	ds_read_b128 v[214:217], v153 offset:38912
	ds_read_b128 v[218:221], v153 offset:39936
	s_waitcnt vmcnt(8)
	s_waitcnt lgkmcnt(0)
	s_barrier
	s_setprio 1
	s_waitcnt lgkmcnt(0)
	v_mfma_f32_16x16x32_bf16 v[128:131], v[144:147], v[190:193], v[128:131]
	v_mfma_f32_16x16x32_bf16 v[124:127], v[158:161], v[190:193], v[124:127]
	v_mfma_f32_16x16x32_bf16 v[112:115], v[144:147], v[198:201], v[112:115]
	v_mfma_f32_16x16x32_bf16 v[108:111], v[158:161], v[198:201], v[108:111]
	v_mfma_f32_16x16x32_bf16 v[96:99], v[144:147], v[206:209], v[96:99]
	v_mfma_f32_16x16x32_bf16 v[92:95], v[158:161], v[206:209], v[92:95]
	v_mfma_f32_16x16x32_bf16 v[80:83], v[144:147], v[214:217], v[80:83]
	v_mfma_f32_16x16x32_bf16 v[76:79], v[158:161], v[214:217], v[76:79]
	v_mfma_f32_16x16x32_bf16 v[128:131], v[154:157], v[194:197], v[128:131]
	v_mfma_f32_16x16x32_bf16 v[124:127], v[162:165], v[194:197], v[124:127]
	v_mfma_f32_16x16x32_bf16 v[112:115], v[154:157], v[202:205], v[112:115]
	v_mfma_f32_16x16x32_bf16 v[108:111], v[162:165], v[202:205], v[108:111]
	v_mfma_f32_16x16x32_bf16 v[96:99], v[154:157], v[210:213], v[96:99]
	v_mfma_f32_16x16x32_bf16 v[92:95], v[162:165], v[210:213], v[92:95]
	v_mfma_f32_16x16x32_bf16 v[80:83], v[154:157], v[218:221], v[80:83]
	v_mfma_f32_16x16x32_bf16 v[76:79], v[162:165], v[218:221], v[76:79]
	s_setprio 0
	s_setprio 1
	v_mfma_f32_16x16x32_bf16 v[120:123], v[166:169], v[190:193], v[120:123]
	v_mfma_f32_16x16x32_bf16 v[116:119], v[174:177], v[190:193], v[116:119]
	v_mfma_f32_16x16x32_bf16 v[104:107], v[166:169], v[198:201], v[104:107]
	v_mfma_f32_16x16x32_bf16 v[100:103], v[174:177], v[198:201], v[100:103]
	v_mfma_f32_16x16x32_bf16 v[88:91], v[166:169], v[206:209], v[88:91]
	v_mfma_f32_16x16x32_bf16 v[84:87], v[174:177], v[206:209], v[84:87]
	v_mfma_f32_16x16x32_bf16 v[72:75], v[166:169], v[214:217], v[72:75]
	v_mfma_f32_16x16x32_bf16 v[68:71], v[174:177], v[214:217], v[68:71]
	v_mfma_f32_16x16x32_bf16 v[120:123], v[170:173], v[194:197], v[120:123]
	v_mfma_f32_16x16x32_bf16 v[116:119], v[186:189], v[194:197], v[116:119]
	v_mfma_f32_16x16x32_bf16 v[104:107], v[170:173], v[202:205], v[104:107]
	v_mfma_f32_16x16x32_bf16 v[100:103], v[186:189], v[202:205], v[100:103]
	v_mfma_f32_16x16x32_bf16 v[88:91], v[170:173], v[210:213], v[88:91]
	v_mfma_f32_16x16x32_bf16 v[84:87], v[186:189], v[210:213], v[84:87]
	v_mfma_f32_16x16x32_bf16 v[72:75], v[170:173], v[218:221], v[72:75]
	v_mfma_f32_16x16x32_bf16 v[68:71], v[186:189], v[218:221], v[68:71]
	s_setprio 0
	s_barrier
	s_add_u32 s28, s28, 0x80
	s_addc_u32 s29, s29, 0
	s_add_i32 m0, s38, 0x18000
	ds_read_b128 v[190:193], v153 offset:49152
	ds_read_b128 v[194:197], v153 offset:50176
	global_load_lds_dwordx4 v136, s[28:29]
	s_add_i32 m0, s38, 0x1a000
	s_add_u32 s98, s98, 0x80
	s_addc_u32 s99, s99, 0
	ds_read_b128 v[198:201], v153 offset:51200
	global_load_lds_dwordx4 v132, s[28:29]
	s_add_i32 m0, s38, 0x1c000
	ds_read_b128 v[202:205], v153 offset:52224
	ds_read_b128 v[206:209], v153 offset:53248
	global_load_lds_dwordx4 v136, s[98:99]
	s_add_i32 m0, s38, 0x1e000
	s_add_u32 s30, s30, 0x80
	s_addc_u32 s31, s31, 0
	ds_read_b128 v[210:213], v153 offset:54272
	ds_read_b128 v[214:217], v153 offset:55296
	global_load_lds_dwordx4 v132, s[98:99]
	s_mov_b32 m0, s45
	ds_read_b128 v[218:221], v153 offset:56320
	global_load_lds_dwordx4 v138, s[30:31]
	s_mov_b32 m0, s46
	s_nop 0
	global_load_lds_dwordx4 v134, s[30:31]
	s_waitcnt vmcnt(8)
	s_waitcnt lgkmcnt(0)
	s_barrier
	s_setprio 1
	s_waitcnt lgkmcnt(0)
	v_mfma_f32_16x16x32_bf16 v[64:67], v[144:147], v[190:193], v[64:67]
	v_mfma_f32_16x16x32_bf16 v[60:63], v[158:161], v[190:193], v[60:63]
	v_mfma_f32_16x16x32_bf16 v[48:51], v[144:147], v[198:201], v[48:51]
	v_mfma_f32_16x16x32_bf16 v[44:47], v[158:161], v[198:201], v[44:47]
	v_mfma_f32_16x16x32_bf16 v[32:35], v[144:147], v[206:209], v[32:35]
	v_mfma_f32_16x16x32_bf16 v[28:31], v[158:161], v[206:209], v[28:31]
	v_mfma_f32_16x16x32_bf16 v[16:19], v[144:147], v[214:217], v[16:19]
	v_mfma_f32_16x16x32_bf16 v[12:15], v[158:161], v[214:217], v[12:15]
	v_mfma_f32_16x16x32_bf16 v[64:67], v[154:157], v[194:197], v[64:67]
	v_mfma_f32_16x16x32_bf16 v[60:63], v[162:165], v[194:197], v[60:63]
	v_mfma_f32_16x16x32_bf16 v[48:51], v[154:157], v[202:205], v[48:51]
	v_mfma_f32_16x16x32_bf16 v[44:47], v[162:165], v[202:205], v[44:47]
	v_mfma_f32_16x16x32_bf16 v[32:35], v[154:157], v[210:213], v[32:35]
	v_mfma_f32_16x16x32_bf16 v[28:31], v[162:165], v[210:213], v[28:31]
	v_mfma_f32_16x16x32_bf16 v[16:19], v[154:157], v[218:221], v[16:19]
	v_mfma_f32_16x16x32_bf16 v[12:15], v[162:165], v[218:221], v[12:15]
	s_setprio 0
	s_setprio 1
	v_mfma_f32_16x16x32_bf16 v[56:59], v[166:169], v[190:193], v[56:59]
	v_mfma_f32_16x16x32_bf16 v[52:55], v[174:177], v[190:193], v[52:55]
	v_mfma_f32_16x16x32_bf16 v[40:43], v[166:169], v[198:201], v[40:43]
	v_mfma_f32_16x16x32_bf16 v[36:39], v[174:177], v[198:201], v[36:39]
	v_mfma_f32_16x16x32_bf16 v[24:27], v[166:169], v[206:209], v[24:27]
	v_mfma_f32_16x16x32_bf16 v[20:23], v[174:177], v[206:209], v[20:23]
	v_mfma_f32_16x16x32_bf16 v[8:11], v[166:169], v[214:217], v[8:11]
	v_mfma_f32_16x16x32_bf16 v[4:7], v[174:177], v[214:217], v[4:7]
	v_mfma_f32_16x16x32_bf16 v[56:59], v[170:173], v[194:197], v[56:59]
	v_mfma_f32_16x16x32_bf16 v[52:55], v[186:189], v[194:197], v[52:55]
	v_mfma_f32_16x16x32_bf16 v[40:43], v[170:173], v[202:205], v[40:43]
	v_mfma_f32_16x16x32_bf16 v[36:39], v[186:189], v[202:205], v[36:39]
	v_mfma_f32_16x16x32_bf16 v[24:27], v[170:173], v[210:213], v[24:27]
	v_mfma_f32_16x16x32_bf16 v[20:23], v[186:189], v[210:213], v[20:23]
	v_mfma_f32_16x16x32_bf16 v[8:11], v[170:173], v[218:221], v[8:11]
	v_mfma_f32_16x16x32_bf16 v[4:7], v[186:189], v[218:221], v[4:7]
	s_setprio 0
	s_barrier
	s_add_i32 s20, s20, 2
	s_add_u32 s10, s10, 0x100
	s_addc_u32 s11, s11, 0
	s_add_u32 s0, s0, 0x100
	s_addc_u32 s1, s1, 0
	s_cmp_gt_u32 s20, 61
	s_cbranch_scc0 .LBB0_1226
	s_and_b64 vcc, exec, s[48:49]
	s_cbranch_vccz .LBB0_1229
	s_barrier

	.amdhsa_kernel _Z8yoco_fwd4Args
		.amdhsa_group_segment_fixed_size 0
		.amdhsa_private_segment_fixed_size 0
		.amdhsa_kernarg_size 376
		.amdhsa_user_sgpr_count 2
		.amdhsa_user_sgpr_dispatch_ptr 0
		.amdhsa_user_sgpr_queue_ptr 0
		.amdhsa_user_sgpr_kernarg_segment_ptr 1
		.amdhsa_user_sgpr_dispatch_id 0
		.amdhsa_user_sgpr_kernarg_preload_length 0
		.amdhsa_user_sgpr_kernarg_preload_offset 0
		.amdhsa_user_sgpr_private_segment_size 0
		.amdhsa_uses_dynamic_stack 0
		.amdhsa_enable_private_segment 0
		.amdhsa_system_sgpr_workgroup_id_x 1
		.amdhsa_system_sgpr_workgroup_id_y 0
		.amdhsa_system_sgpr_workgroup_id_z 0
		.amdhsa_system_sgpr_workgroup_info 0
		.amdhsa_system_vgpr_workitem_id 0
		.amdhsa_next_free_vgpr 256
		.amdhsa_next_free_sgpr 102
		.amdhsa_accum_offset 256
		.amdhsa_reserve_vcc 1
		.amdhsa_float_round_mode_32 0
		.amdhsa_float_round_mode_16_64 0
		.amdhsa_float_denorm_mode_32 3
		.amdhsa_float_denorm_mode_16_64 3
		.amdhsa_dx10_clamp 1
		.amdhsa_ieee_mode 1
		.amdhsa_fp16_overflow 0
		.amdhsa_tg_split 0
		.amdhsa_exception_fp_ieee_invalid_op 0
		.amdhsa_exception_fp_denorm_src 0
		.amdhsa_exception_fp_ieee_div_zero 0
		.amdhsa_exception_fp_ieee_overflow 0
		.amdhsa_exception_fp_ieee_underflow 0
		.amdhsa_exception_fp_ieee_inexact 0
		.amdhsa_exception_int_div_zero 0
	.end_amdhsa_kernel

amdhsa.kernels:
  - .agpr_count:     0
    .args:
      - .offset:         0
        .size:           120
        .value_kind:     by_value
      - .offset:         120
        .size:           4
        .value_kind:     hidden_block_count_x
      - .offset:         124
        .size:           4
        .value_kind:     hidden_block_count_y
      - .offset:         128
        .size:           4
        .value_kind:     hidden_block_count_z
      - .offset:         132
        .size:           2
        .value_kind:     hidden_group_size_x
      - .offset:         134
        .size:           2
        .value_kind:     hidden_group_size_y
      - .offset:         136
        .size:           2
        .value_kind:     hidden_group_size_z
      - .offset:         138
        .size:           2
        .value_kind:     hidden_remainder_x
      - .offset:         140
        .size:           2
        .value_kind:     hidden_remainder_y
      - .offset:         142
        .size:           2
        .value_kind:     hidden_remainder_z
      - .offset:         160
        .size:           8
        .value_kind:     hidden_global_offset_x
      - .offset:         168
        .size:           8
        .value_kind:     hidden_global_offset_y
      - .offset:         176
        .size:           8
        .value_kind:     hidden_global_offset_z
      - .offset:         184
        .size:           2
        .value_kind:     hidden_grid_dims
      - .offset:         240
        .size:           4
        .value_kind:     hidden_dynamic_lds_size
    .group_segment_fixed_size: 0
    .kernarg_segment_align: 8
    .kernarg_segment_size: 376
    .language:       OpenCL C
    .language_version:
      - 2
      - 0
    .max_flat_workgroup_size: 512
    .name:           _Z8yoco_fwd4Args
    .private_segment_fixed_size: 0
    .sgpr_count:     108
    .sgpr_spill_count: 130
    .symbol:         _Z8yoco_fwd4Args.kd
    .uniform_work_group_size: 1
    .uses_dynamic_stack: false
    .vgpr_count:     256
    .vgpr_spill_count: 0
    .wavefront_size: 64
